# LayerNorm XB stores write-through (sc1): no dirty lines left for the full barrier's L2 write-back
# speedup vs baseline: 1.0038x; 1.0038x over previous
; __device__ __forceinline__ unsigned rne_w7(float v) { const unsigned u = __float_as_uint(v); return (u + 0xFFFFu + ((u >> 17) & 1u)) & 0xFFFE0000u; }
; __device__ __forceinline__ unsigned cvt_pk_w7(float lo, float hi) { return (rne_w7(lo) >> 16) | rne_w7(hi); }
.LBB0_188:
	s_or_b64 exec, exec, s[4:5]
	v_pk_mul_f32 v[78:79], v[98:99], v[78:79] op_sel_hi:[0,1]
	v_pk_fma_f32 v[78:79], v[6:7], v[78:79], v[14:15]
	v_pk_mul_f32 v[88:89], v[98:99], v[88:89] op_sel_hi:[0,1]
	v_bfe_u32 v112, v78, 17, 1
	v_add3_u32 v78, v78, v112, s55
	v_bfe_u32 v112, v79, 17, 1
	v_add3_u32 v79, v79, v112, s55
	v_pk_fma_f32 v[88:89], v[8:9], v[88:89], v[16:17]
	v_lshrrev_b32_e32 v78, 16, v78
	v_and_b32_e32 v79, 0xfffe0000, v79
	v_and_or_b32 v78, v78, s57, v79
	v_bfe_u32 v79, v88, 17, 1
	v_add3_u32 v79, v88, v79, s55
	v_bfe_u32 v88, v89, 17, 1
	v_pk_mul_f32 v[80:81], v[98:99], v[80:81] op_sel_hi:[0,1]
	v_add3_u32 v88, v89, v88, s55
	v_pk_fma_f32 v[80:81], v[80:81], v[2:3], v[10:11]
	v_lshrrev_b32_e32 v79, 16, v79
	v_and_b32_e32 v88, 0xfffe0000, v88
	v_and_or_b32 v79, v79, s57, v88
	v_bfe_u32 v88, v80, 17, 1
	v_add3_u32 v80, v80, v88, s55
	v_bfe_u32 v88, v81, 17, 1
	v_pk_mul_f32 v[86:87], v[98:99], v[86:87] op_sel_hi:[0,1]
	v_add3_u32 v81, v81, v88, s55
	v_pk_fma_f32 v[86:87], v[86:87], v[4:5], v[12:13]
	v_lshrrev_b32_e32 v80, 16, v80
	v_and_b32_e32 v81, 0xfffe0000, v81
	v_and_or_b32 v80, v80, s57, v81
	v_bfe_u32 v81, v86, 17, 1
	v_add3_u32 v81, v86, v81, s55
	v_bfe_u32 v86, v87, 17, 1
	v_add3_u32 v86, v87, v86, s55
	v_pk_mul_f32 v[74:75], v[98:99], v[74:75] op_sel_hi:[0,1]
	v_lshrrev_b32_e32 v81, 16, v81
	v_and_b32_e32 v86, 0xfffe0000, v86
	v_pk_fma_f32 v[74:75], v[22:23], v[74:75], v[30:31]
	s_lshl_b64 s[4:5], s[12:13], 11
	v_and_or_b32 v81, v81, s57, v86
	v_bfe_u32 v86, v74, 17, 1
	v_lshl_add_u64 v[110:111], s[4:5], 1, v[84:85]
	v_add3_u32 v74, v74, v86, s55
	v_bfe_u32 v86, v75, 17, 1
	global_store_dwordx4 v[110:111], v[78:81], off sc1
	v_add3_u32 v75, v75, v86, s55
	v_lshrrev_b32_e32 v74, 16, v74
	v_pk_mul_f32 v[78:79], v[98:99], v[92:93] op_sel_hi:[0,1]
	v_pk_fma_f32 v[78:79], v[24:25], v[78:79], v[32:33]
	v_and_b32_e32 v75, 0xfffe0000, v75
	v_and_or_b32 v74, v74, s57, v75
	v_bfe_u32 v75, v78, 17, 1
	v_add3_u32 v75, v78, v75, s55
	v_bfe_u32 v78, v79, 17, 1
	v_pk_mul_f32 v[76:77], v[98:99], v[76:77] op_sel_hi:[0,1]
	v_add3_u32 v78, v79, v78, s55
	v_pk_fma_f32 v[76:77], v[76:77], v[18:19], v[26:27]
	v_lshrrev_b32_e32 v75, 16, v75
	v_and_b32_e32 v78, 0xfffe0000, v78
	v_and_or_b32 v75, v75, s57, v78
	v_bfe_u32 v78, v76, 17, 1
	v_add3_u32 v76, v76, v78, s55
	v_bfe_u32 v78, v77, 17, 1
	v_pk_mul_f32 v[80:81], v[98:99], v[90:91] op_sel_hi:[0,1]
	v_add3_u32 v77, v77, v78, s55
	v_pk_fma_f32 v[80:81], v[80:81], v[20:21], v[28:29]
	v_lshrrev_b32_e32 v76, 16, v76
	v_and_b32_e32 v77, 0xfffe0000, v77
	v_and_or_b32 v76, v76, s57, v77
	v_bfe_u32 v77, v80, 17, 1
	v_bfe_u32 v78, v81, 17, 1
	v_add3_u32 v77, v80, v77, s55
	v_add3_u32 v78, v81, v78, s55
	v_pk_mul_f32 v[70:71], v[98:99], v[70:71] op_sel_hi:[0,1]
	v_lshrrev_b32_e32 v77, 16, v77
	v_and_b32_e32 v78, 0xfffe0000, v78
	v_pk_fma_f32 v[70:71], v[38:39], v[70:71], v[46:47]
	v_and_or_b32 v77, v77, s57, v78
	v_bfe_u32 v78, v70, 17, 1
	v_add3_u32 v70, v70, v78, s55
	v_bfe_u32 v78, v71, 17, 1
	global_store_dwordx4 v[110:111], v[74:77], off offset:1024 sc1
	v_add3_u32 v71, v71, v78, s55
	v_lshrrev_b32_e32 v70, 16, v70
	v_pk_mul_f32 v[74:75], v[98:99], v[96:97] op_sel_hi:[0,1]
	v_pk_fma_f32 v[74:75], v[40:41], v[74:75], v[48:49]
	v_and_b32_e32 v71, 0xfffe0000, v71
	v_and_or_b32 v70, v70, s57, v71
	v_bfe_u32 v71, v74, 17, 1
	v_add3_u32 v71, v74, v71, s55
	v_bfe_u32 v74, v75, 17, 1
	v_pk_mul_f32 v[72:73], v[98:99], v[72:73] op_sel_hi:[0,1]
	v_add3_u32 v74, v75, v74, s55
	v_pk_fma_f32 v[72:73], v[72:73], v[34:35], v[42:43]
	v_lshrrev_b32_e32 v71, 16, v71
	v_and_b32_e32 v74, 0xfffe0000, v74
	v_and_or_b32 v71, v71, s57, v74
	v_bfe_u32 v74, v72, 17, 1
	v_add3_u32 v72, v72, v74, s55
	v_bfe_u32 v74, v73, 17, 1
	v_pk_mul_f32 v[76:77], v[98:99], v[94:95] op_sel_hi:[0,1]
	v_add3_u32 v73, v73, v74, s55
	v_pk_fma_f32 v[76:77], v[76:77], v[36:37], v[44:45]
	v_lshrrev_b32_e32 v72, 16, v72
	v_and_b32_e32 v73, 0xfffe0000, v73
	v_and_or_b32 v72, v72, s57, v73
	v_bfe_u32 v73, v76, 17, 1
	v_bfe_u32 v74, v77, 17, 1
	v_add3_u32 v73, v76, v73, s55
	v_add3_u32 v74, v77, v74, s55
	v_pk_mul_f32 v[66:67], v[98:99], v[66:67] op_sel_hi:[0,1]
	v_lshrrev_b32_e32 v73, 16, v73
	v_and_b32_e32 v74, 0xfffe0000, v74
	v_pk_fma_f32 v[66:67], v[54:55], v[66:67], v[62:63]
	v_and_or_b32 v73, v73, s57, v74
	v_bfe_u32 v74, v66, 17, 1
	v_add3_u32 v66, v66, v74, s55
	v_bfe_u32 v74, v67, 17, 1
	global_store_dwordx4 v[110:111], v[70:73], off offset:2048 sc1
	v_add3_u32 v67, v67, v74, s55
	v_lshrrev_b32_e32 v66, 16, v66
	v_pk_mul_f32 v[70:71], v[98:99], v[102:103] op_sel_hi:[0,1]
	v_pk_fma_f32 v[70:71], v[56:57], v[70:71], v[64:65]
	v_and_b32_e32 v67, 0xfffe0000, v67
	v_and_or_b32 v66, v66, s57, v67
	v_bfe_u32 v67, v70, 17, 1
	v_add3_u32 v67, v70, v67, s55
	v_bfe_u32 v70, v71, 17, 1
	v_pk_mul_f32 v[68:69], v[98:99], v[68:69] op_sel_hi:[0,1]
	v_add3_u32 v70, v71, v70, s55
	v_pk_fma_f32 v[68:69], v[68:69], v[50:51], v[58:59]
	v_lshrrev_b32_e32 v67, 16, v67
	v_and_b32_e32 v70, 0xfffe0000, v70
	v_and_or_b32 v67, v67, s57, v70
	v_bfe_u32 v70, v68, 17, 1
	v_add3_u32 v68, v68, v70, s55
	v_bfe_u32 v70, v69, 17, 1
	v_pk_mul_f32 v[72:73], v[98:99], v[100:101] op_sel_hi:[0,1]
	v_add3_u32 v69, v69, v70, s55
	v_pk_fma_f32 v[72:73], v[72:73], v[52:53], v[60:61]
	v_lshrrev_b32_e32 v68, 16, v68
	v_and_b32_e32 v69, 0xfffe0000, v69
	v_and_or_b32 v68, v68, s57, v69
	v_bfe_u32 v69, v72, 17, 1
	v_bfe_u32 v70, v73, 17, 1
	v_add3_u32 v69, v72, v69, s55
	v_add3_u32 v70, v73, v70, s55
	v_lshrrev_b32_e32 v69, 16, v69
	v_and_b32_e32 v70, 0xfffe0000, v70
	s_add_i32 s15, s15, 1
	s_add_i32 s17, s17, s43
	s_add_i32 s16, s16, -1
	v_and_or_b32 v69, v69, s57, v70
	s_cmp_lg_u32 s16, 0
	global_store_dwordx4 v[110:111], v[66:69], off offset:3072 sc1
	s_cbranch_scc0 .LBB0_193

; __device__ __forceinline__ unsigned rne_w7(float v) { const unsigned u = __float_as_uint(v); return (u + 0xFFFFu + ((u >> 17) & 1u)) & 0xFFFE0000u; }
; __device__ __forceinline__ unsigned cvt_pk_w7(float lo, float hi) { return (rne_w7(lo) >> 16) | rne_w7(hi); }
.LBB0_907:
	s_or_b64 exec, exec, s[4:5]
	v_pk_mul_f32 v[78:79], v[98:99], v[78:79] op_sel_hi:[0,1]
	v_pk_fma_f32 v[78:79], v[6:7], v[78:79], v[14:15]
	v_pk_mul_f32 v[88:89], v[98:99], v[88:89] op_sel_hi:[0,1]
	v_bfe_u32 v112, v78, 17, 1
	v_add3_u32 v78, v78, v112, s55
	v_bfe_u32 v112, v79, 17, 1
	v_add3_u32 v79, v79, v112, s55
	v_pk_fma_f32 v[88:89], v[8:9], v[88:89], v[16:17]
	v_lshrrev_b32_e32 v78, 16, v78
	v_and_b32_e32 v79, 0xfffe0000, v79
	v_and_or_b32 v78, v78, s57, v79
	v_bfe_u32 v79, v88, 17, 1
	v_add3_u32 v79, v88, v79, s55
	v_bfe_u32 v88, v89, 17, 1
	v_pk_mul_f32 v[80:81], v[98:99], v[80:81] op_sel_hi:[0,1]
	v_add3_u32 v88, v89, v88, s55
	v_pk_fma_f32 v[80:81], v[80:81], v[2:3], v[10:11]
	v_lshrrev_b32_e32 v79, 16, v79
	v_and_b32_e32 v88, 0xfffe0000, v88
	v_and_or_b32 v79, v79, s57, v88
	v_bfe_u32 v88, v80, 17, 1
	v_add3_u32 v80, v80, v88, s55
	v_bfe_u32 v88, v81, 17, 1
	v_pk_mul_f32 v[86:87], v[98:99], v[86:87] op_sel_hi:[0,1]
	v_add3_u32 v81, v81, v88, s55
	v_pk_fma_f32 v[86:87], v[86:87], v[4:5], v[12:13]
	v_lshrrev_b32_e32 v80, 16, v80
	v_and_b32_e32 v81, 0xfffe0000, v81
	v_and_or_b32 v80, v80, s57, v81
	v_bfe_u32 v81, v86, 17, 1
	v_add3_u32 v81, v86, v81, s55
	v_bfe_u32 v86, v87, 17, 1
	v_add3_u32 v86, v87, v86, s55
	v_pk_mul_f32 v[74:75], v[98:99], v[74:75] op_sel_hi:[0,1]
	v_lshrrev_b32_e32 v81, 16, v81
	v_and_b32_e32 v86, 0xfffe0000, v86
	v_pk_fma_f32 v[74:75], v[22:23], v[74:75], v[30:31]
	s_lshl_b64 s[4:5], s[6:7], 11
	v_and_or_b32 v81, v81, s57, v86
	v_bfe_u32 v86, v74, 17, 1
	v_lshl_add_u64 v[110:111], s[4:5], 1, v[84:85]
	v_add3_u32 v74, v74, v86, s55
	v_bfe_u32 v86, v75, 17, 1
	global_store_dwordx4 v[110:111], v[78:81], off sc1
	v_add3_u32 v75, v75, v86, s55
	v_lshrrev_b32_e32 v74, 16, v74
	v_pk_mul_f32 v[78:79], v[98:99], v[92:93] op_sel_hi:[0,1]
	v_pk_fma_f32 v[78:79], v[24:25], v[78:79], v[32:33]
	v_and_b32_e32 v75, 0xfffe0000, v75
	v_and_or_b32 v74, v74, s57, v75
	v_bfe_u32 v75, v78, 17, 1
	v_add3_u32 v75, v78, v75, s55
	v_bfe_u32 v78, v79, 17, 1
	v_pk_mul_f32 v[76:77], v[98:99], v[76:77] op_sel_hi:[0,1]
	v_add3_u32 v78, v79, v78, s55
	v_pk_fma_f32 v[76:77], v[76:77], v[18:19], v[26:27]
	v_lshrrev_b32_e32 v75, 16, v75
	v_and_b32_e32 v78, 0xfffe0000, v78
	v_and_or_b32 v75, v75, s57, v78
	v_bfe_u32 v78, v76, 17, 1
	v_add3_u32 v76, v76, v78, s55
	v_bfe_u32 v78, v77, 17, 1
	v_pk_mul_f32 v[80:81], v[98:99], v[90:91] op_sel_hi:[0,1]
	v_add3_u32 v77, v77, v78, s55
	v_pk_fma_f32 v[80:81], v[80:81], v[20:21], v[28:29]
	v_lshrrev_b32_e32 v76, 16, v76
	v_and_b32_e32 v77, 0xfffe0000, v77
	v_and_or_b32 v76, v76, s57, v77
	v_bfe_u32 v77, v80, 17, 1
	v_bfe_u32 v78, v81, 17, 1
	v_add3_u32 v77, v80, v77, s55
	v_add3_u32 v78, v81, v78, s55
	v_pk_mul_f32 v[70:71], v[98:99], v[70:71] op_sel_hi:[0,1]
	v_lshrrev_b32_e32 v77, 16, v77
	v_and_b32_e32 v78, 0xfffe0000, v78
	v_pk_fma_f32 v[70:71], v[38:39], v[70:71], v[46:47]
	v_and_or_b32 v77, v77, s57, v78
	v_bfe_u32 v78, v70, 17, 1
	v_add3_u32 v70, v70, v78, s55
	v_bfe_u32 v78, v71, 17, 1
	global_store_dwordx4 v[110:111], v[74:77], off offset:1024 sc1
	v_add3_u32 v71, v71, v78, s55
	v_lshrrev_b32_e32 v70, 16, v70
	v_pk_mul_f32 v[74:75], v[98:99], v[96:97] op_sel_hi:[0,1]
	v_pk_fma_f32 v[74:75], v[40:41], v[74:75], v[48:49]
	v_and_b32_e32 v71, 0xfffe0000, v71
	v_and_or_b32 v70, v70, s57, v71
	v_bfe_u32 v71, v74, 17, 1
	v_add3_u32 v71, v74, v71, s55
	v_bfe_u32 v74, v75, 17, 1
	v_pk_mul_f32 v[72:73], v[98:99], v[72:73] op_sel_hi:[0,1]
	v_add3_u32 v74, v75, v74, s55
	v_pk_fma_f32 v[72:73], v[72:73], v[34:35], v[42:43]
	v_lshrrev_b32_e32 v71, 16, v71
	v_and_b32_e32 v74, 0xfffe0000, v74
	v_and_or_b32 v71, v71, s57, v74
	v_bfe_u32 v74, v72, 17, 1
	v_add3_u32 v72, v72, v74, s55
	v_bfe_u32 v74, v73, 17, 1
	v_pk_mul_f32 v[76:77], v[98:99], v[94:95] op_sel_hi:[0,1]
	v_add3_u32 v73, v73, v74, s55
	v_pk_fma_f32 v[76:77], v[76:77], v[36:37], v[44:45]
	v_lshrrev_b32_e32 v72, 16, v72
	v_and_b32_e32 v73, 0xfffe0000, v73
	v_and_or_b32 v72, v72, s57, v73
	v_bfe_u32 v73, v76, 17, 1
	v_bfe_u32 v74, v77, 17, 1
	v_add3_u32 v73, v76, v73, s55
	v_add3_u32 v74, v77, v74, s55
	v_pk_mul_f32 v[66:67], v[98:99], v[66:67] op_sel_hi:[0,1]
	v_lshrrev_b32_e32 v73, 16, v73
	v_and_b32_e32 v74, 0xfffe0000, v74
	v_pk_fma_f32 v[66:67], v[54:55], v[66:67], v[62:63]
	v_and_or_b32 v73, v73, s57, v74
	v_bfe_u32 v74, v66, 17, 1
	v_add3_u32 v66, v66, v74, s55
	v_bfe_u32 v74, v67, 17, 1
	global_store_dwordx4 v[110:111], v[70:73], off offset:2048 sc1
	v_add3_u32 v67, v67, v74, s55
	v_lshrrev_b32_e32 v66, 16, v66
	v_pk_mul_f32 v[70:71], v[98:99], v[102:103] op_sel_hi:[0,1]
	v_pk_fma_f32 v[70:71], v[56:57], v[70:71], v[64:65]
	v_and_b32_e32 v67, 0xfffe0000, v67
	v_and_or_b32 v66, v66, s57, v67
	v_bfe_u32 v67, v70, 17, 1
	v_add3_u32 v67, v70, v67, s55
	v_bfe_u32 v70, v71, 17, 1
	v_pk_mul_f32 v[68:69], v[98:99], v[68:69] op_sel_hi:[0,1]
	v_add3_u32 v70, v71, v70, s55
	v_pk_fma_f32 v[68:69], v[68:69], v[50:51], v[58:59]
	v_lshrrev_b32_e32 v67, 16, v67
	v_and_b32_e32 v70, 0xfffe0000, v70
	v_and_or_b32 v67, v67, s57, v70
	v_bfe_u32 v70, v68, 17, 1
	v_add3_u32 v68, v68, v70, s55
	v_bfe_u32 v70, v69, 17, 1
	v_pk_mul_f32 v[72:73], v[98:99], v[100:101] op_sel_hi:[0,1]
	v_add3_u32 v69, v69, v70, s55
	v_pk_fma_f32 v[72:73], v[72:73], v[52:53], v[60:61]
	v_lshrrev_b32_e32 v68, 16, v68
	v_and_b32_e32 v69, 0xfffe0000, v69
	v_and_or_b32 v68, v68, s57, v69
	v_bfe_u32 v69, v72, 17, 1
	v_bfe_u32 v70, v73, 17, 1
	v_add3_u32 v69, v72, v69, s55
	v_add3_u32 v70, v73, v70, s55
	v_lshrrev_b32_e32 v69, 16, v69
	v_and_b32_e32 v70, 0xfffe0000, v70
	s_add_i32 s9, s9, 1
	s_add_i32 s13, s13, s43
	s_add_i32 s12, s12, -1
	v_and_or_b32 v69, v69, s57, v70
	s_cmp_eq_u32 s12, 0
	global_store_dwordx4 v[110:111], v[66:69], off offset:3072 sc1
	s_cbranch_scc1 .LBB0_912
